# S5 step loops hand-written: u rows double-buffered from LDS, two FMA chains per step
# baseline (speedup 1.0000x reference)
.LBB0_279:
	v_add_u32_e32 v41, s4, v35
	s_addk_i32 s4, 0x200
	ds_read_b128 v[176:179], v41
	ds_read_b128 v[180:183], v41 offset:16
	ds_read_b128 v[184:187], v41 offset:32
	ds_read_b128 v[188:191], v41 offset:48
	ds_read_b128 v[192:195], v41 offset:64
	ds_read_b128 v[196:199], v41 offset:80
	ds_read_b128 v[200:203], v41 offset:96
	ds_read_b128 v[204:207], v41 offset:112
	ds_read_b128 v[208:211], v41 offset:128
	ds_read_b128 v[212:215], v41 offset:144
	ds_read_b128 v[216:219], v41 offset:160
	ds_read_b128 v[220:223], v41 offset:176
	ds_read_b128 v[144:147], v41 offset:192
	ds_read_b128 v[148:151], v41 offset:208
	ds_read_b128 v[152:155], v41 offset:224
	ds_read_b128 v[156:159], v41 offset:240
	s_waitcnt lgkmcnt(8)
	v_pk_fma_f32 v[126:127], v[176:177], v[108:109], 0 op_sel_hi:[0,1,0]
	v_pk_fma_f32 v[124:125], v[184:185], v[22:23], 0 op_sel_hi:[0,1,0]
	v_pk_fma_f32 v[126:127], v[176:177], v[28:29], v[126:127] op_sel:[1,0,0]
	v_pk_fma_f32 v[124:125], v[184:185], v[12:13], v[124:125] op_sel:[1,0,0]
	v_pk_fma_f32 v[126:127], v[178:179], v[24:25], v[126:127] op_sel_hi:[0,1,1]
	v_pk_fma_f32 v[124:125], v[186:187], v[8:9], v[124:125] op_sel_hi:[0,1,1]
	v_pk_fma_f32 v[126:127], v[178:179], v[26:27], v[126:127] op_sel:[1,0,0]
	v_pk_fma_f32 v[124:125], v[186:187], v[10:11], v[124:125] op_sel:[1,0,0]
	v_pk_fma_f32 v[126:127], v[180:181], v[30:31], v[126:127] op_sel_hi:[0,1,1]
	v_pk_fma_f32 v[124:125], v[188:189], v[14:15], v[124:125] op_sel_hi:[0,1,1]
	v_pk_fma_f32 v[126:127], v[180:181], v[20:21], v[126:127] op_sel:[1,0,0]
	v_pk_fma_f32 v[124:125], v[188:189], v[4:5], v[124:125] op_sel:[1,0,0]
	v_pk_fma_f32 v[126:127], v[182:183], v[16:17], v[126:127] op_sel_hi:[0,1,1]
	v_pk_fma_f32 v[124:125], v[190:191], v[0:1], v[124:125] op_sel_hi:[0,1,1]
	v_pk_fma_f32 v[126:127], v[182:183], v[18:19], v[126:127] op_sel:[1,0,0]
	v_pk_fma_f32 v[124:125], v[190:191], v[2:3], v[124:125] op_sel:[1,0,0]
	v_pk_mul_f32 v[122:123], v[106:107], v[6:7] op_sel:[0,1] op_sel_hi:[1,0]
	v_pk_add_f32 v[126:127], v[126:127], v[124:125]
	v_pk_fma_f32 v[112:113], v[104:105], v[6:7], v[122:123] neg_lo:[0,0,1] neg_hi:[0,0,1]
	v_pk_fma_f32 v[6:7], v[104:105], v[6:7], v[122:123]
	s_nop 0
	v_mov_b32_e32 v113, v7
	v_pk_add_f32 v[6:7], v[112:113], v[126:127]
	v_pk_fma_f32 v[126:127], v[192:193], v[108:109], 0 op_sel_hi:[0,1,0]
	v_pk_fma_f32 v[124:125], v[200:201], v[22:23], 0 op_sel_hi:[0,1,0]
	v_pk_fma_f32 v[126:127], v[192:193], v[28:29], v[126:127] op_sel:[1,0,0]
	v_pk_fma_f32 v[124:125], v[200:201], v[12:13], v[124:125] op_sel:[1,0,0]
	v_pk_fma_f32 v[126:127], v[194:195], v[24:25], v[126:127] op_sel_hi:[0,1,1]
	v_pk_fma_f32 v[124:125], v[202:203], v[8:9], v[124:125] op_sel_hi:[0,1,1]
	v_pk_fma_f32 v[126:127], v[194:195], v[26:27], v[126:127] op_sel:[1,0,0]
	v_pk_fma_f32 v[124:125], v[202:203], v[10:11], v[124:125] op_sel:[1,0,0]
	v_pk_fma_f32 v[126:127], v[196:197], v[30:31], v[126:127] op_sel_hi:[0,1,1]
	v_pk_fma_f32 v[124:125], v[204:205], v[14:15], v[124:125] op_sel_hi:[0,1,1]
	v_pk_fma_f32 v[126:127], v[196:197], v[20:21], v[126:127] op_sel:[1,0,0]
	v_pk_fma_f32 v[124:125], v[204:205], v[4:5], v[124:125] op_sel:[1,0,0]
	v_pk_fma_f32 v[126:127], v[198:199], v[16:17], v[126:127] op_sel_hi:[0,1,1]
	v_pk_fma_f32 v[124:125], v[206:207], v[0:1], v[124:125] op_sel_hi:[0,1,1]
	v_pk_fma_f32 v[126:127], v[198:199], v[18:19], v[126:127] op_sel:[1,0,0]
	v_pk_fma_f32 v[124:125], v[206:207], v[2:3], v[124:125] op_sel:[1,0,0]
	v_pk_mul_f32 v[122:123], v[106:107], v[6:7] op_sel:[0,1] op_sel_hi:[1,0]
	v_pk_add_f32 v[126:127], v[126:127], v[124:125]
	v_pk_fma_f32 v[112:113], v[104:105], v[6:7], v[122:123] neg_lo:[0,0,1] neg_hi:[0,0,1]
	v_pk_fma_f32 v[6:7], v[104:105], v[6:7], v[122:123]
	s_nop 0
	v_mov_b32_e32 v113, v7
	v_pk_add_f32 v[6:7], v[112:113], v[126:127]
	ds_read_b128 v[176:179], v41 offset:256
	ds_read_b128 v[180:183], v41 offset:272
	ds_read_b128 v[184:187], v41 offset:288
	ds_read_b128 v[188:191], v41 offset:304
	ds_read_b128 v[192:195], v41 offset:320
	ds_read_b128 v[196:199], v41 offset:336
	ds_read_b128 v[200:203], v41 offset:352
	ds_read_b128 v[204:207], v41 offset:368
	s_waitcnt lgkmcnt(8)
	v_pk_fma_f32 v[126:127], v[208:209], v[108:109], 0 op_sel_hi:[0,1,0]
	v_pk_fma_f32 v[124:125], v[216:217], v[22:23], 0 op_sel_hi:[0,1,0]
	v_pk_fma_f32 v[126:127], v[208:209], v[28:29], v[126:127] op_sel:[1,0,0]
	v_pk_fma_f32 v[124:125], v[216:217], v[12:13], v[124:125] op_sel:[1,0,0]
	v_pk_fma_f32 v[126:127], v[210:211], v[24:25], v[126:127] op_sel_hi:[0,1,1]
	v_pk_fma_f32 v[124:125], v[218:219], v[8:9], v[124:125] op_sel_hi:[0,1,1]
	v_pk_fma_f32 v[126:127], v[210:211], v[26:27], v[126:127] op_sel:[1,0,0]
	v_pk_fma_f32 v[124:125], v[218:219], v[10:11], v[124:125] op_sel:[1,0,0]
	v_pk_fma_f32 v[126:127], v[212:213], v[30:31], v[126:127] op_sel_hi:[0,1,1]
	v_pk_fma_f32 v[124:125], v[220:221], v[14:15], v[124:125] op_sel_hi:[0,1,1]
	v_pk_fma_f32 v[126:127], v[212:213], v[20:21], v[126:127] op_sel:[1,0,0]
	v_pk_fma_f32 v[124:125], v[220:221], v[4:5], v[124:125] op_sel:[1,0,0]
	v_pk_fma_f32 v[126:127], v[214:215], v[16:17], v[126:127] op_sel_hi:[0,1,1]
	v_pk_fma_f32 v[124:125], v[222:223], v[0:1], v[124:125] op_sel_hi:[0,1,1]
	v_pk_fma_f32 v[126:127], v[214:215], v[18:19], v[126:127] op_sel:[1,0,0]
	v_pk_fma_f32 v[124:125], v[222:223], v[2:3], v[124:125] op_sel:[1,0,0]
	v_pk_mul_f32 v[122:123], v[106:107], v[6:7] op_sel:[0,1] op_sel_hi:[1,0]
	v_pk_add_f32 v[126:127], v[126:127], v[124:125]
	v_pk_fma_f32 v[112:113], v[104:105], v[6:7], v[122:123] neg_lo:[0,0,1] neg_hi:[0,0,1]
	v_pk_fma_f32 v[6:7], v[104:105], v[6:7], v[122:123]
	s_nop 0
	v_mov_b32_e32 v113, v7
	v_pk_add_f32 v[6:7], v[112:113], v[126:127]
	v_pk_fma_f32 v[126:127], v[144:145], v[108:109], 0 op_sel_hi:[0,1,0]
	v_pk_fma_f32 v[124:125], v[152:153], v[22:23], 0 op_sel_hi:[0,1,0]
	v_pk_fma_f32 v[126:127], v[144:145], v[28:29], v[126:127] op_sel:[1,0,0]
	v_pk_fma_f32 v[124:125], v[152:153], v[12:13], v[124:125] op_sel:[1,0,0]
	v_pk_fma_f32 v[126:127], v[146:147], v[24:25], v[126:127] op_sel_hi:[0,1,1]
	v_pk_fma_f32 v[124:125], v[154:155], v[8:9], v[124:125] op_sel_hi:[0,1,1]
	v_pk_fma_f32 v[126:127], v[146:147], v[26:27], v[126:127] op_sel:[1,0,0]
	v_pk_fma_f32 v[124:125], v[154:155], v[10:11], v[124:125] op_sel:[1,0,0]
	v_pk_fma_f32 v[126:127], v[148:149], v[30:31], v[126:127] op_sel_hi:[0,1,1]
	v_pk_fma_f32 v[124:125], v[156:157], v[14:15], v[124:125] op_sel_hi:[0,1,1]
	v_pk_fma_f32 v[126:127], v[148:149], v[20:21], v[126:127] op_sel:[1,0,0]
	v_pk_fma_f32 v[124:125], v[156:157], v[4:5], v[124:125] op_sel:[1,0,0]
	v_pk_fma_f32 v[126:127], v[150:151], v[16:17], v[126:127] op_sel_hi:[0,1,1]
	v_pk_fma_f32 v[124:125], v[158:159], v[0:1], v[124:125] op_sel_hi:[0,1,1]
	v_pk_fma_f32 v[126:127], v[150:151], v[18:19], v[126:127] op_sel:[1,0,0]
	v_pk_fma_f32 v[124:125], v[158:159], v[2:3], v[124:125] op_sel:[1,0,0]
	v_pk_mul_f32 v[122:123], v[106:107], v[6:7] op_sel:[0,1] op_sel_hi:[1,0]
	v_pk_add_f32 v[126:127], v[126:127], v[124:125]
	v_pk_fma_f32 v[112:113], v[104:105], v[6:7], v[122:123] neg_lo:[0,0,1] neg_hi:[0,0,1]
	v_pk_fma_f32 v[6:7], v[104:105], v[6:7], v[122:123]
	s_nop 0
	v_mov_b32_e32 v113, v7
	v_pk_add_f32 v[6:7], v[112:113], v[126:127]
	ds_read_b128 v[208:211], v41 offset:384
	ds_read_b128 v[212:215], v41 offset:400
	ds_read_b128 v[216:219], v41 offset:416
	ds_read_b128 v[220:223], v41 offset:432
	ds_read_b128 v[144:147], v41 offset:448
	ds_read_b128 v[148:151], v41 offset:464
	ds_read_b128 v[152:155], v41 offset:480
	ds_read_b128 v[156:159], v41 offset:496
	s_waitcnt lgkmcnt(8)
	v_pk_fma_f32 v[126:127], v[176:177], v[108:109], 0 op_sel_hi:[0,1,0]
	v_pk_fma_f32 v[124:125], v[184:185], v[22:23], 0 op_sel_hi:[0,1,0]
	v_pk_fma_f32 v[126:127], v[176:177], v[28:29], v[126:127] op_sel:[1,0,0]
	v_pk_fma_f32 v[124:125], v[184:185], v[12:13], v[124:125] op_sel:[1,0,0]
	v_pk_fma_f32 v[126:127], v[178:179], v[24:25], v[126:127] op_sel_hi:[0,1,1]
	v_pk_fma_f32 v[124:125], v[186:187], v[8:9], v[124:125] op_sel_hi:[0,1,1]
	v_pk_fma_f32 v[126:127], v[178:179], v[26:27], v[126:127] op_sel:[1,0,0]
	v_pk_fma_f32 v[124:125], v[186:187], v[10:11], v[124:125] op_sel:[1,0,0]
	v_pk_fma_f32 v[126:127], v[180:181], v[30:31], v[126:127] op_sel_hi:[0,1,1]
	v_pk_fma_f32 v[124:125], v[188:189], v[14:15], v[124:125] op_sel_hi:[0,1,1]
	v_pk_fma_f32 v[126:127], v[180:181], v[20:21], v[126:127] op_sel:[1,0,0]
	v_pk_fma_f32 v[124:125], v[188:189], v[4:5], v[124:125] op_sel:[1,0,0]
	v_pk_fma_f32 v[126:127], v[182:183], v[16:17], v[126:127] op_sel_hi:[0,1,1]
	v_pk_fma_f32 v[124:125], v[190:191], v[0:1], v[124:125] op_sel_hi:[0,1,1]
	v_pk_fma_f32 v[126:127], v[182:183], v[18:19], v[126:127] op_sel:[1,0,0]
	v_pk_fma_f32 v[124:125], v[190:191], v[2:3], v[124:125] op_sel:[1,0,0]
	v_pk_mul_f32 v[122:123], v[106:107], v[6:7] op_sel:[0,1] op_sel_hi:[1,0]
	v_pk_add_f32 v[126:127], v[126:127], v[124:125]
	v_pk_fma_f32 v[112:113], v[104:105], v[6:7], v[122:123] neg_lo:[0,0,1] neg_hi:[0,0,1]
	v_pk_fma_f32 v[6:7], v[104:105], v[6:7], v[122:123]
	s_nop 0
	v_mov_b32_e32 v113, v7
	v_pk_add_f32 v[6:7], v[112:113], v[126:127]
	v_pk_fma_f32 v[126:127], v[192:193], v[108:109], 0 op_sel_hi:[0,1,0]
	v_pk_fma_f32 v[124:125], v[200:201], v[22:23], 0 op_sel_hi:[0,1,0]
	v_pk_fma_f32 v[126:127], v[192:193], v[28:29], v[126:127] op_sel:[1,0,0]
	v_pk_fma_f32 v[124:125], v[200:201], v[12:13], v[124:125] op_sel:[1,0,0]
	v_pk_fma_f32 v[126:127], v[194:195], v[24:25], v[126:127] op_sel_hi:[0,1,1]
	v_pk_fma_f32 v[124:125], v[202:203], v[8:9], v[124:125] op_sel_hi:[0,1,1]
	v_pk_fma_f32 v[126:127], v[194:195], v[26:27], v[126:127] op_sel:[1,0,0]
	v_pk_fma_f32 v[124:125], v[202:203], v[10:11], v[124:125] op_sel:[1,0,0]
	v_pk_fma_f32 v[126:127], v[196:197], v[30:31], v[126:127] op_sel_hi:[0,1,1]
	v_pk_fma_f32 v[124:125], v[204:205], v[14:15], v[124:125] op_sel_hi:[0,1,1]
	v_pk_fma_f32 v[126:127], v[196:197], v[20:21], v[126:127] op_sel:[1,0,0]
	v_pk_fma_f32 v[124:125], v[204:205], v[4:5], v[124:125] op_sel:[1,0,0]
	v_pk_fma_f32 v[126:127], v[198:199], v[16:17], v[126:127] op_sel_hi:[0,1,1]
	v_pk_fma_f32 v[124:125], v[206:207], v[0:1], v[124:125] op_sel_hi:[0,1,1]
	v_pk_fma_f32 v[126:127], v[198:199], v[18:19], v[126:127] op_sel:[1,0,0]
	v_pk_fma_f32 v[124:125], v[206:207], v[2:3], v[124:125] op_sel:[1,0,0]
	v_pk_mul_f32 v[122:123], v[106:107], v[6:7] op_sel:[0,1] op_sel_hi:[1,0]
	v_pk_add_f32 v[126:127], v[126:127], v[124:125]
	v_pk_fma_f32 v[112:113], v[104:105], v[6:7], v[122:123] neg_lo:[0,0,1] neg_hi:[0,0,1]
	v_pk_fma_f32 v[6:7], v[104:105], v[6:7], v[122:123]
	s_nop 0
	v_mov_b32_e32 v113, v7
	v_pk_add_f32 v[6:7], v[112:113], v[126:127]
	s_waitcnt lgkmcnt(0)
	v_pk_fma_f32 v[126:127], v[208:209], v[108:109], 0 op_sel_hi:[0,1,0]
	v_pk_fma_f32 v[124:125], v[216:217], v[22:23], 0 op_sel_hi:[0,1,0]
	v_pk_fma_f32 v[126:127], v[208:209], v[28:29], v[126:127] op_sel:[1,0,0]
	v_pk_fma_f32 v[124:125], v[216:217], v[12:13], v[124:125] op_sel:[1,0,0]
	v_pk_fma_f32 v[126:127], v[210:211], v[24:25], v[126:127] op_sel_hi:[0,1,1]
	v_pk_fma_f32 v[124:125], v[218:219], v[8:9], v[124:125] op_sel_hi:[0,1,1]
	v_pk_fma_f32 v[126:127], v[210:211], v[26:27], v[126:127] op_sel:[1,0,0]
	v_pk_fma_f32 v[124:125], v[218:219], v[10:11], v[124:125] op_sel:[1,0,0]
	v_pk_fma_f32 v[126:127], v[212:213], v[30:31], v[126:127] op_sel_hi:[0,1,1]
	v_pk_fma_f32 v[124:125], v[220:221], v[14:15], v[124:125] op_sel_hi:[0,1,1]
	v_pk_fma_f32 v[126:127], v[212:213], v[20:21], v[126:127] op_sel:[1,0,0]
	v_pk_fma_f32 v[124:125], v[220:221], v[4:5], v[124:125] op_sel:[1,0,0]
	v_pk_fma_f32 v[126:127], v[214:215], v[16:17], v[126:127] op_sel_hi:[0,1,1]
	v_pk_fma_f32 v[124:125], v[222:223], v[0:1], v[124:125] op_sel_hi:[0,1,1]
	v_pk_fma_f32 v[126:127], v[214:215], v[18:19], v[126:127] op_sel:[1,0,0]
	v_pk_fma_f32 v[124:125], v[222:223], v[2:3], v[124:125] op_sel:[1,0,0]
	v_pk_mul_f32 v[122:123], v[106:107], v[6:7] op_sel:[0,1] op_sel_hi:[1,0]
	v_pk_add_f32 v[126:127], v[126:127], v[124:125]
	v_pk_fma_f32 v[112:113], v[104:105], v[6:7], v[122:123] neg_lo:[0,0,1] neg_hi:[0,0,1]
	v_pk_fma_f32 v[6:7], v[104:105], v[6:7], v[122:123]
	s_nop 0
	v_mov_b32_e32 v113, v7
	v_pk_add_f32 v[6:7], v[112:113], v[126:127]
	v_pk_fma_f32 v[126:127], v[144:145], v[108:109], 0 op_sel_hi:[0,1,0]
	v_pk_fma_f32 v[124:125], v[152:153], v[22:23], 0 op_sel_hi:[0,1,0]
	v_pk_fma_f32 v[126:127], v[144:145], v[28:29], v[126:127] op_sel:[1,0,0]
	v_pk_fma_f32 v[124:125], v[152:153], v[12:13], v[124:125] op_sel:[1,0,0]
	v_pk_fma_f32 v[126:127], v[146:147], v[24:25], v[126:127] op_sel_hi:[0,1,1]
	v_pk_fma_f32 v[124:125], v[154:155], v[8:9], v[124:125] op_sel_hi:[0,1,1]
	v_pk_fma_f32 v[126:127], v[146:147], v[26:27], v[126:127] op_sel:[1,0,0]
	v_pk_fma_f32 v[124:125], v[154:155], v[10:11], v[124:125] op_sel:[1,0,0]
	v_pk_fma_f32 v[126:127], v[148:149], v[30:31], v[126:127] op_sel_hi:[0,1,1]
	v_pk_fma_f32 v[124:125], v[156:157], v[14:15], v[124:125] op_sel_hi:[0,1,1]
	v_pk_fma_f32 v[126:127], v[148:149], v[20:21], v[126:127] op_sel:[1,0,0]
	v_pk_fma_f32 v[124:125], v[156:157], v[4:5], v[124:125] op_sel:[1,0,0]
	v_pk_fma_f32 v[126:127], v[150:151], v[16:17], v[126:127] op_sel_hi:[0,1,1]
	v_pk_fma_f32 v[124:125], v[158:159], v[0:1], v[124:125] op_sel_hi:[0,1,1]
	v_pk_fma_f32 v[126:127], v[150:151], v[18:19], v[126:127] op_sel:[1,0,0]
	v_pk_fma_f32 v[124:125], v[158:159], v[2:3], v[124:125] op_sel:[1,0,0]
	v_pk_mul_f32 v[122:123], v[106:107], v[6:7] op_sel:[0,1] op_sel_hi:[1,0]
	v_pk_add_f32 v[126:127], v[126:127], v[124:125]
	v_pk_fma_f32 v[112:113], v[104:105], v[6:7], v[122:123] neg_lo:[0,0,1] neg_hi:[0,0,1]
	v_pk_fma_f32 v[6:7], v[104:105], v[6:7], v[122:123]
	s_nop 0
	v_mov_b32_e32 v113, v7
	v_pk_add_f32 v[6:7], v[112:113], v[126:127]
	s_cmpk_lg_i32 s4, 0x1000
	s_cbranch_scc1 .LBB0_279
	s_waitcnt lgkmcnt(0)
	s_load_dwordx2 s[4:5], s[0:1], 0x150
	v_ashrrev_i32_e32 v103, 31, v102
	v_lshlrev_b64 v[0:1], 9, v[102:103]
	v_mov_b32_e32 v97, v169
	s_waitcnt lgkmcnt(0)
	v_lshl_add_u64 v[0:1], s[4:5], 0, v[0:1]
	v_lshl_add_u64 v[0:1], v[0:1], 0, v[96:97]
	v_add_co_u32_e32 v0, vcc, 0x2d381000, v0
	s_mov_b64 s[4:5], 0
	s_nop 0
	v_addc_co_u32_e32 v1, vcc, 0, v1, vcc
	global_store_dwordx2 v[0:1], v[6:7], off offset:2048

.LBB0_880:
	v_add_u32_e32 v248, s4, v110
	v_add_u32_e32 v248, 0x11800, v248
	s_addk_i32 s4, 0x200
	ds_read_b128 v[176:179], v248
	ds_read_b128 v[180:183], v248 offset:16
	ds_read_b128 v[184:187], v248 offset:32
	ds_read_b128 v[188:191], v248 offset:48
	ds_read_b128 v[192:195], v248 offset:64
	ds_read_b128 v[196:199], v248 offset:80
	ds_read_b128 v[200:203], v248 offset:96
	ds_read_b128 v[204:207], v248 offset:112
	ds_read_b128 v[208:211], v248 offset:128
	ds_read_b128 v[212:215], v248 offset:144
	ds_read_b128 v[216:219], v248 offset:160
	ds_read_b128 v[220:223], v248 offset:176
	ds_read_b128 v[156:159], v248 offset:192
	ds_read_b128 v[160:163], v248 offset:208
	ds_read_b128 v[164:167], v248 offset:224
	ds_read_b128 v[232:235], v248 offset:240
	s_waitcnt lgkmcnt(8)
	v_pk_fma_f32 v[240:241], v[176:177], v[54:55], 0 op_sel_hi:[0,1,0]
	v_pk_fma_f32 v[242:243], v[184:185], v[72:73], 0 op_sel_hi:[0,1,0]
	v_pk_fma_f32 v[240:241], v[176:177], v[56:57], v[240:241] op_sel:[1,0,0]
	v_pk_fma_f32 v[242:243], v[184:185], v[74:75], v[242:243] op_sel:[1,0,0]
	v_pk_fma_f32 v[240:241], v[178:179], v[58:59], v[240:241] op_sel_hi:[0,1,1]
	v_pk_fma_f32 v[242:243], v[186:187], v[76:77], v[242:243] op_sel_hi:[0,1,1]
	v_pk_fma_f32 v[240:241], v[178:179], v[60:61], v[240:241] op_sel:[1,0,0]
	v_pk_fma_f32 v[242:243], v[186:187], v[78:79], v[242:243] op_sel:[1,0,0]
	v_pk_fma_f32 v[240:241], v[180:181], v[62:63], v[240:241] op_sel_hi:[0,1,1]
	v_pk_fma_f32 v[242:243], v[188:189], v[80:81], v[242:243] op_sel_hi:[0,1,1]
	v_pk_fma_f32 v[240:241], v[180:181], v[64:65], v[240:241] op_sel:[1,0,0]
	v_pk_fma_f32 v[242:243], v[188:189], v[82:83], v[242:243] op_sel:[1,0,0]
	v_pk_fma_f32 v[240:241], v[182:183], v[68:69], v[240:241] op_sel_hi:[0,1,1]
	v_pk_fma_f32 v[242:243], v[190:191], v[84:85], v[242:243] op_sel_hi:[0,1,1]
	v_pk_fma_f32 v[240:241], v[182:183], v[70:71], v[240:241] op_sel:[1,0,0]
	v_pk_fma_f32 v[242:243], v[190:191], v[86:87], v[242:243] op_sel:[1,0,0]
	v_pk_mul_f32 v[246:247], v[52:53], v[66:67]
	v_pk_add_f32 v[240:241], v[240:241], v[242:243]
	v_pk_fma_f32 v[244:245], v[88:89], v[66:67], v[246:247] op_sel:[0,0,1] op_sel_hi:[1,1,0]
	v_pk_fma_f32 v[66:67], v[88:89], v[66:67], v[246:247] op_sel:[0,0,1] op_sel_hi:[1,1,0] neg_lo:[0,0,1] neg_hi:[0,0,1]
	s_nop 0
	v_mov_b32_e32 v245, v67
	v_pk_add_f32 v[66:67], v[244:245], v[240:241]
	s_nop 0
	v_cvt_pk_bf16_f32 v249, v66, v67
	ds_write_b16_d16_hi v41, v249
	ds_write_b16 v41, v249 offset:128
	v_pk_fma_f32 v[240:241], v[192:193], v[54:55], 0 op_sel_hi:[0,1,0]
	v_pk_fma_f32 v[242:243], v[200:201], v[72:73], 0 op_sel_hi:[0,1,0]
	v_pk_fma_f32 v[240:241], v[192:193], v[56:57], v[240:241] op_sel:[1,0,0]
	v_pk_fma_f32 v[242:243], v[200:201], v[74:75], v[242:243] op_sel:[1,0,0]
	v_pk_fma_f32 v[240:241], v[194:195], v[58:59], v[240:241] op_sel_hi:[0,1,1]
	v_pk_fma_f32 v[242:243], v[202:203], v[76:77], v[242:243] op_sel_hi:[0,1,1]
	v_pk_fma_f32 v[240:241], v[194:195], v[60:61], v[240:241] op_sel:[1,0,0]
	v_pk_fma_f32 v[242:243], v[202:203], v[78:79], v[242:243] op_sel:[1,0,0]
	v_pk_fma_f32 v[240:241], v[196:197], v[62:63], v[240:241] op_sel_hi:[0,1,1]
	v_pk_fma_f32 v[242:243], v[204:205], v[80:81], v[242:243] op_sel_hi:[0,1,1]
	v_pk_fma_f32 v[240:241], v[196:197], v[64:65], v[240:241] op_sel:[1,0,0]
	v_pk_fma_f32 v[242:243], v[204:205], v[82:83], v[242:243] op_sel:[1,0,0]
	v_pk_fma_f32 v[240:241], v[198:199], v[68:69], v[240:241] op_sel_hi:[0,1,1]
	v_pk_fma_f32 v[242:243], v[206:207], v[84:85], v[242:243] op_sel_hi:[0,1,1]
	v_pk_fma_f32 v[240:241], v[198:199], v[70:71], v[240:241] op_sel:[1,0,0]
	v_pk_fma_f32 v[242:243], v[206:207], v[86:87], v[242:243] op_sel:[1,0,0]
	v_pk_mul_f32 v[246:247], v[52:53], v[66:67]
	v_pk_add_f32 v[240:241], v[240:241], v[242:243]
	v_pk_fma_f32 v[244:245], v[88:89], v[66:67], v[246:247] op_sel:[0,0,1] op_sel_hi:[1,1,0]
	v_pk_fma_f32 v[66:67], v[88:89], v[66:67], v[246:247] op_sel:[0,0,1] op_sel_hi:[1,1,0] neg_lo:[0,0,1] neg_hi:[0,0,1]
	s_nop 0
	v_mov_b32_e32 v245, v67
	v_pk_add_f32 v[66:67], v[244:245], v[240:241]
	s_nop 0
	v_cvt_pk_bf16_f32 v249, v66, v67
	ds_write_b16_d16_hi v41, v249 offset:272
	ds_write_b16 v41, v249 offset:400
	ds_read_b128 v[176:179], v248 offset:256
	ds_read_b128 v[180:183], v248 offset:272
	ds_read_b128 v[184:187], v248 offset:288
	ds_read_b128 v[188:191], v248 offset:304
	ds_read_b128 v[192:195], v248 offset:320
	ds_read_b128 v[196:199], v248 offset:336
	ds_read_b128 v[200:203], v248 offset:352
	ds_read_b128 v[204:207], v248 offset:368
	s_waitcnt lgkmcnt(12)
	v_pk_fma_f32 v[240:241], v[208:209], v[54:55], 0 op_sel_hi:[0,1,0]
	v_pk_fma_f32 v[242:243], v[216:217], v[72:73], 0 op_sel_hi:[0,1,0]
	v_pk_fma_f32 v[240:241], v[208:209], v[56:57], v[240:241] op_sel:[1,0,0]
	v_pk_fma_f32 v[242:243], v[216:217], v[74:75], v[242:243] op_sel:[1,0,0]
	v_pk_fma_f32 v[240:241], v[210:211], v[58:59], v[240:241] op_sel_hi:[0,1,1]
	v_pk_fma_f32 v[242:243], v[218:219], v[76:77], v[242:243] op_sel_hi:[0,1,1]
	v_pk_fma_f32 v[240:241], v[210:211], v[60:61], v[240:241] op_sel:[1,0,0]
	v_pk_fma_f32 v[242:243], v[218:219], v[78:79], v[242:243] op_sel:[1,0,0]
	v_pk_fma_f32 v[240:241], v[212:213], v[62:63], v[240:241] op_sel_hi:[0,1,1]
	v_pk_fma_f32 v[242:243], v[220:221], v[80:81], v[242:243] op_sel_hi:[0,1,1]
	v_pk_fma_f32 v[240:241], v[212:213], v[64:65], v[240:241] op_sel:[1,0,0]
	v_pk_fma_f32 v[242:243], v[220:221], v[82:83], v[242:243] op_sel:[1,0,0]
	v_pk_fma_f32 v[240:241], v[214:215], v[68:69], v[240:241] op_sel_hi:[0,1,1]
	v_pk_fma_f32 v[242:243], v[222:223], v[84:85], v[242:243] op_sel_hi:[0,1,1]
	v_pk_fma_f32 v[240:241], v[214:215], v[70:71], v[240:241] op_sel:[1,0,0]
	v_pk_fma_f32 v[242:243], v[222:223], v[86:87], v[242:243] op_sel:[1,0,0]
	v_pk_mul_f32 v[246:247], v[52:53], v[66:67]
	v_pk_add_f32 v[240:241], v[240:241], v[242:243]
	v_pk_fma_f32 v[244:245], v[88:89], v[66:67], v[246:247] op_sel:[0,0,1] op_sel_hi:[1,1,0]
	v_pk_fma_f32 v[66:67], v[88:89], v[66:67], v[246:247] op_sel:[0,0,1] op_sel_hi:[1,1,0] neg_lo:[0,0,1] neg_hi:[0,0,1]
	s_nop 0
	v_mov_b32_e32 v245, v67
	v_pk_add_f32 v[66:67], v[244:245], v[240:241]
	s_nop 0
	v_cvt_pk_bf16_f32 v249, v66, v67
	ds_write_b16_d16_hi v41, v249 offset:544
	ds_write_b16 v41, v249 offset:672
	v_pk_fma_f32 v[240:241], v[156:157], v[54:55], 0 op_sel_hi:[0,1,0]
	v_pk_fma_f32 v[242:243], v[164:165], v[72:73], 0 op_sel_hi:[0,1,0]
	v_pk_fma_f32 v[240:241], v[156:157], v[56:57], v[240:241] op_sel:[1,0,0]
	v_pk_fma_f32 v[242:243], v[164:165], v[74:75], v[242:243] op_sel:[1,0,0]
	v_pk_fma_f32 v[240:241], v[158:159], v[58:59], v[240:241] op_sel_hi:[0,1,1]
	v_pk_fma_f32 v[242:243], v[166:167], v[76:77], v[242:243] op_sel_hi:[0,1,1]
	v_pk_fma_f32 v[240:241], v[158:159], v[60:61], v[240:241] op_sel:[1,0,0]
	v_pk_fma_f32 v[242:243], v[166:167], v[78:79], v[242:243] op_sel:[1,0,0]
	v_pk_fma_f32 v[240:241], v[160:161], v[62:63], v[240:241] op_sel_hi:[0,1,1]
	v_pk_fma_f32 v[242:243], v[232:233], v[80:81], v[242:243] op_sel_hi:[0,1,1]
	v_pk_fma_f32 v[240:241], v[160:161], v[64:65], v[240:241] op_sel:[1,0,0]
	v_pk_fma_f32 v[242:243], v[232:233], v[82:83], v[242:243] op_sel:[1,0,0]
	v_pk_fma_f32 v[240:241], v[162:163], v[68:69], v[240:241] op_sel_hi:[0,1,1]
	v_pk_fma_f32 v[242:243], v[234:235], v[84:85], v[242:243] op_sel_hi:[0,1,1]
	v_pk_fma_f32 v[240:241], v[162:163], v[70:71], v[240:241] op_sel:[1,0,0]
	v_pk_fma_f32 v[242:243], v[234:235], v[86:87], v[242:243] op_sel:[1,0,0]
	v_pk_mul_f32 v[246:247], v[52:53], v[66:67]
	v_pk_add_f32 v[240:241], v[240:241], v[242:243]
	v_pk_fma_f32 v[244:245], v[88:89], v[66:67], v[246:247] op_sel:[0,0,1] op_sel_hi:[1,1,0]
	v_pk_fma_f32 v[66:67], v[88:89], v[66:67], v[246:247] op_sel:[0,0,1] op_sel_hi:[1,1,0] neg_lo:[0,0,1] neg_hi:[0,0,1]
	s_nop 0
	v_mov_b32_e32 v245, v67
	v_pk_add_f32 v[66:67], v[244:245], v[240:241]
	s_nop 0
	v_cvt_pk_bf16_f32 v249, v66, v67
	ds_write_b16_d16_hi v41, v249 offset:816
	ds_write_b16 v41, v249 offset:944
	ds_read_b128 v[208:211], v248 offset:384
	ds_read_b128 v[212:215], v248 offset:400
	ds_read_b128 v[216:219], v248 offset:416
	ds_read_b128 v[220:223], v248 offset:432
	ds_read_b128 v[156:159], v248 offset:448
	ds_read_b128 v[160:163], v248 offset:464
	ds_read_b128 v[164:167], v248 offset:480
	ds_read_b128 v[232:235], v248 offset:496
	s_waitcnt lgkmcnt(12)
	v_pk_fma_f32 v[240:241], v[176:177], v[54:55], 0 op_sel_hi:[0,1,0]
	v_pk_fma_f32 v[242:243], v[184:185], v[72:73], 0 op_sel_hi:[0,1,0]
	v_pk_fma_f32 v[240:241], v[176:177], v[56:57], v[240:241] op_sel:[1,0,0]
	v_pk_fma_f32 v[242:243], v[184:185], v[74:75], v[242:243] op_sel:[1,0,0]
	v_pk_fma_f32 v[240:241], v[178:179], v[58:59], v[240:241] op_sel_hi:[0,1,1]
	v_pk_fma_f32 v[242:243], v[186:187], v[76:77], v[242:243] op_sel_hi:[0,1,1]
	v_pk_fma_f32 v[240:241], v[178:179], v[60:61], v[240:241] op_sel:[1,0,0]
	v_pk_fma_f32 v[242:243], v[186:187], v[78:79], v[242:243] op_sel:[1,0,0]
	v_pk_fma_f32 v[240:241], v[180:181], v[62:63], v[240:241] op_sel_hi:[0,1,1]
	v_pk_fma_f32 v[242:243], v[188:189], v[80:81], v[242:243] op_sel_hi:[0,1,1]
	v_pk_fma_f32 v[240:241], v[180:181], v[64:65], v[240:241] op_sel:[1,0,0]
	v_pk_fma_f32 v[242:243], v[188:189], v[82:83], v[242:243] op_sel:[1,0,0]
	v_pk_fma_f32 v[240:241], v[182:183], v[68:69], v[240:241] op_sel_hi:[0,1,1]
	v_pk_fma_f32 v[242:243], v[190:191], v[84:85], v[242:243] op_sel_hi:[0,1,1]
	v_pk_fma_f32 v[240:241], v[182:183], v[70:71], v[240:241] op_sel:[1,0,0]
	v_pk_fma_f32 v[242:243], v[190:191], v[86:87], v[242:243] op_sel:[1,0,0]
	v_pk_mul_f32 v[246:247], v[52:53], v[66:67]
	v_pk_add_f32 v[240:241], v[240:241], v[242:243]
	v_pk_fma_f32 v[244:245], v[88:89], v[66:67], v[246:247] op_sel:[0,0,1] op_sel_hi:[1,1,0]
	v_pk_fma_f32 v[66:67], v[88:89], v[66:67], v[246:247] op_sel:[0,0,1] op_sel_hi:[1,1,0] neg_lo:[0,0,1] neg_hi:[0,0,1]
	s_nop 0
	v_mov_b32_e32 v245, v67
	v_pk_add_f32 v[66:67], v[244:245], v[240:241]
	s_nop 0
	v_cvt_pk_bf16_f32 v249, v66, v67
	ds_write_b16_d16_hi v41, v249 offset:1088
	ds_write_b16 v41, v249 offset:1216
	v_pk_fma_f32 v[240:241], v[192:193], v[54:55], 0 op_sel_hi:[0,1,0]
	v_pk_fma_f32 v[242:243], v[200:201], v[72:73], 0 op_sel_hi:[0,1,0]
	v_pk_fma_f32 v[240:241], v[192:193], v[56:57], v[240:241] op_sel:[1,0,0]
	v_pk_fma_f32 v[242:243], v[200:201], v[74:75], v[242:243] op_sel:[1,0,0]
	v_pk_fma_f32 v[240:241], v[194:195], v[58:59], v[240:241] op_sel_hi:[0,1,1]
	v_pk_fma_f32 v[242:243], v[202:203], v[76:77], v[242:243] op_sel_hi:[0,1,1]
	v_pk_fma_f32 v[240:241], v[194:195], v[60:61], v[240:241] op_sel:[1,0,0]
	v_pk_fma_f32 v[242:243], v[202:203], v[78:79], v[242:243] op_sel:[1,0,0]
	v_pk_fma_f32 v[240:241], v[196:197], v[62:63], v[240:241] op_sel_hi:[0,1,1]
	v_pk_fma_f32 v[242:243], v[204:205], v[80:81], v[242:243] op_sel_hi:[0,1,1]
	v_pk_fma_f32 v[240:241], v[196:197], v[64:65], v[240:241] op_sel:[1,0,0]
	v_pk_fma_f32 v[242:243], v[204:205], v[82:83], v[242:243] op_sel:[1,0,0]
	v_pk_fma_f32 v[240:241], v[198:199], v[68:69], v[240:241] op_sel_hi:[0,1,1]
	v_pk_fma_f32 v[242:243], v[206:207], v[84:85], v[242:243] op_sel_hi:[0,1,1]
	v_pk_fma_f32 v[240:241], v[198:199], v[70:71], v[240:241] op_sel:[1,0,0]
	v_pk_fma_f32 v[242:243], v[206:207], v[86:87], v[242:243] op_sel:[1,0,0]
	v_pk_mul_f32 v[246:247], v[52:53], v[66:67]
	v_pk_add_f32 v[240:241], v[240:241], v[242:243]
	v_pk_fma_f32 v[244:245], v[88:89], v[66:67], v[246:247] op_sel:[0,0,1] op_sel_hi:[1,1,0]
	v_pk_fma_f32 v[66:67], v[88:89], v[66:67], v[246:247] op_sel:[0,0,1] op_sel_hi:[1,1,0] neg_lo:[0,0,1] neg_hi:[0,0,1]
	s_nop 0
	v_mov_b32_e32 v245, v67
	v_pk_add_f32 v[66:67], v[244:245], v[240:241]
	s_nop 0
	v_cvt_pk_bf16_f32 v249, v66, v67
	ds_write_b16_d16_hi v41, v249 offset:1360
	ds_write_b16 v41, v249 offset:1488
	s_waitcnt lgkmcnt(4)
	v_pk_fma_f32 v[240:241], v[208:209], v[54:55], 0 op_sel_hi:[0,1,0]
	v_pk_fma_f32 v[242:243], v[216:217], v[72:73], 0 op_sel_hi:[0,1,0]
	v_pk_fma_f32 v[240:241], v[208:209], v[56:57], v[240:241] op_sel:[1,0,0]
	v_pk_fma_f32 v[242:243], v[216:217], v[74:75], v[242:243] op_sel:[1,0,0]
	v_pk_fma_f32 v[240:241], v[210:211], v[58:59], v[240:241] op_sel_hi:[0,1,1]
	v_pk_fma_f32 v[242:243], v[218:219], v[76:77], v[242:243] op_sel_hi:[0,1,1]
	v_pk_fma_f32 v[240:241], v[210:211], v[60:61], v[240:241] op_sel:[1,0,0]
	v_pk_fma_f32 v[242:243], v[218:219], v[78:79], v[242:243] op_sel:[1,0,0]
	v_pk_fma_f32 v[240:241], v[212:213], v[62:63], v[240:241] op_sel_hi:[0,1,1]
	v_pk_fma_f32 v[242:243], v[220:221], v[80:81], v[242:243] op_sel_hi:[0,1,1]
	v_pk_fma_f32 v[240:241], v[212:213], v[64:65], v[240:241] op_sel:[1,0,0]
	v_pk_fma_f32 v[242:243], v[220:221], v[82:83], v[242:243] op_sel:[1,0,0]
	v_pk_fma_f32 v[240:241], v[214:215], v[68:69], v[240:241] op_sel_hi:[0,1,1]
	v_pk_fma_f32 v[242:243], v[222:223], v[84:85], v[242:243] op_sel_hi:[0,1,1]
	v_pk_fma_f32 v[240:241], v[214:215], v[70:71], v[240:241] op_sel:[1,0,0]
	v_pk_fma_f32 v[242:243], v[222:223], v[86:87], v[242:243] op_sel:[1,0,0]
	v_pk_mul_f32 v[246:247], v[52:53], v[66:67]
	v_pk_add_f32 v[240:241], v[240:241], v[242:243]
	v_pk_fma_f32 v[244:245], v[88:89], v[66:67], v[246:247] op_sel:[0,0,1] op_sel_hi:[1,1,0]
	v_pk_fma_f32 v[66:67], v[88:89], v[66:67], v[246:247] op_sel:[0,0,1] op_sel_hi:[1,1,0] neg_lo:[0,0,1] neg_hi:[0,0,1]
	s_nop 0
	v_mov_b32_e32 v245, v67
	v_pk_add_f32 v[66:67], v[244:245], v[240:241]
	s_nop 0
	v_cvt_pk_bf16_f32 v249, v66, v67
	ds_write_b16_d16_hi v41, v249 offset:1632
	ds_write_b16 v41, v249 offset:1760
	v_pk_fma_f32 v[240:241], v[156:157], v[54:55], 0 op_sel_hi:[0,1,0]
	v_pk_fma_f32 v[242:243], v[164:165], v[72:73], 0 op_sel_hi:[0,1,0]
	v_pk_fma_f32 v[240:241], v[156:157], v[56:57], v[240:241] op_sel:[1,0,0]
	v_pk_fma_f32 v[242:243], v[164:165], v[74:75], v[242:243] op_sel:[1,0,0]
	v_pk_fma_f32 v[240:241], v[158:159], v[58:59], v[240:241] op_sel_hi:[0,1,1]
	v_pk_fma_f32 v[242:243], v[166:167], v[76:77], v[242:243] op_sel_hi:[0,1,1]
	v_pk_fma_f32 v[240:241], v[158:159], v[60:61], v[240:241] op_sel:[1,0,0]
	v_pk_fma_f32 v[242:243], v[166:167], v[78:79], v[242:243] op_sel:[1,0,0]
	v_pk_fma_f32 v[240:241], v[160:161], v[62:63], v[240:241] op_sel_hi:[0,1,1]
	v_pk_fma_f32 v[242:243], v[232:233], v[80:81], v[242:243] op_sel_hi:[0,1,1]
	v_pk_fma_f32 v[240:241], v[160:161], v[64:65], v[240:241] op_sel:[1,0,0]
	v_pk_fma_f32 v[242:243], v[232:233], v[82:83], v[242:243] op_sel:[1,0,0]
	v_pk_fma_f32 v[240:241], v[162:163], v[68:69], v[240:241] op_sel_hi:[0,1,1]
	v_pk_fma_f32 v[242:243], v[234:235], v[84:85], v[242:243] op_sel_hi:[0,1,1]
	v_pk_fma_f32 v[240:241], v[162:163], v[70:71], v[240:241] op_sel:[1,0,0]
	v_pk_fma_f32 v[242:243], v[234:235], v[86:87], v[242:243] op_sel:[1,0,0]
	v_pk_mul_f32 v[246:247], v[52:53], v[66:67]
	v_pk_add_f32 v[240:241], v[240:241], v[242:243]
	v_pk_fma_f32 v[244:245], v[88:89], v[66:67], v[246:247] op_sel:[0,0,1] op_sel_hi:[1,1,0]
	v_pk_fma_f32 v[66:67], v[88:89], v[66:67], v[246:247] op_sel:[0,0,1] op_sel_hi:[1,1,0] neg_lo:[0,0,1] neg_hi:[0,0,1]
	s_nop 0
	v_mov_b32_e32 v245, v67
	v_pk_add_f32 v[66:67], v[244:245], v[240:241]
	s_nop 0
	v_cvt_pk_bf16_f32 v249, v66, v67
	ds_write_b16_d16_hi v41, v249 offset:1904
	ds_write_b16 v41, v249 offset:2032
	v_add_u32_e32 v41, 0x880, v41
	s_cmp_lg_u32 s4, 0
	s_cbranch_scc1 .LBB0_880
	s_waitcnt vmcnt(11)
	v_bfe_u32 v49, v7, 16, 1
	v_bfe_u32 v129, v6, 16, 1
	v_bfe_u32 v130, v5, 16, 1
	v_bfe_u32 v131, v4, 16, 1
	s_waitcnt vmcnt(5)
	v_pk_add_f32 v[8:9], v[8:9], 0 neg_lo:[1,1] neg_hi:[1,1]
	v_pk_add_f32 v[10:11], v[10:11], 0 neg_lo:[1,1] neg_hi:[1,1]
	v_add3_u32 v131, v4, v131, s43
	v_add3_u32 v130, v5, v130, s43
	v_add3_u32 v129, v6, v129, s43
	v_add3_u32 v49, v7, v49, s43
	v_bfe_u32 v4, v18, 16, 1
	v_bfe_u32 v5, v39, 16, 1
	v_bfe_u32 v6, v17, 16, 1
	v_bfe_u32 v7, v16, 16, 1
	s_waitcnt vmcnt(2)
	v_pk_add_f32 v[12:13], v[12:13], 0 neg_lo:[1,1] neg_hi:[1,1]
	v_pk_add_f32 v[14:15], v[14:15], 0 neg_lo:[1,1] neg_hi:[1,1]
	v_add3_u32 v16, v16, v7, s43
	v_add3_u32 v17, v17, v6, s43
	v_add3_u32 v39, v39, v5, s43
	v_add3_u32 v18, v18, v4, s43
	v_bfe_u32 v4, v11, 16, 1
	v_bfe_u32 v5, v10, 16, 1
	v_bfe_u32 v6, v9, 16, 1
	v_bfe_u32 v7, v8, 16, 1
	v_add3_u32 v135, v8, v7, s43
	v_add3_u32 v136, v9, v6, s43
	v_add3_u32 v137, v10, v5, s43
	v_add3_u32 v138, v11, v4, s43
	v_bfe_u32 v4, v15, 16, 1
	v_bfe_u32 v5, v14, 16, 1
	v_bfe_u32 v6, v13, 16, 1
	v_bfe_u32 v7, v12, 16, 1
	v_add3_u32 v139, v12, v7, s43
	v_add3_u32 v140, v13, v6, s43
	v_add3_u32 v141, v14, v5, s43
	v_add3_u32 v142, v15, v4, s43
	s_waitcnt lgkmcnt(0)
	ds_read_b128 v[4:7], v128
	ds_read_b128 v[12:15], v128 offset:64
	v_bfe_u32 v41, v22, 16, 1
	v_bfe_u32 v43, v19, 16, 1
	v_pk_add_f32 v[26:27], v[26:27], 0 neg_lo:[1,1] neg_hi:[1,1]
	v_bfe_u32 v45, v21, 16, 1
	v_bfe_u32 v47, v20, 16, 1
	v_add3_u32 v19, v19, v43, s43
	v_add3_u32 v41, v22, v41, s43
	v_bfe_u32 v22, v1, 16, 1
	v_bfe_u32 v43, v0, 16, 1
	v_pk_add_f32 v[24:25], v[24:25], 0 neg_lo:[1,1] neg_hi:[1,1]
	s_waitcnt vmcnt(1)
	v_pk_add_f32 v[30:31], v[30:31], 0 neg_lo:[1,1] neg_hi:[1,1]
	v_add3_u32 v47, v20, v47, s43
	v_add3_u32 v45, v21, v45, s43
	v_bfe_u32 v20, v3, 16, 1
	v_bfe_u32 v21, v2, 16, 1
	v_add3_u32 v43, v0, v43, s43
	v_add3_u32 v132, v1, v22, s43
	v_bfe_u32 v0, v27, 16, 1
	v_bfe_u32 v1, v26, 16, 1
	v_pk_add_f32 v[28:29], v[28:29], 0 neg_lo:[1,1] neg_hi:[1,1]
	v_lshl_add_u64 v[90:91], v[90:91], 1, s[6:7]
	v_add3_u32 v133, v2, v21, s43
	v_add3_u32 v134, v3, v20, s43
	v_bfe_u32 v2, v25, 16, 1
	v_bfe_u32 v3, v24, 16, 1
	v_add3_u32 v26, v26, v1, s43
	v_add3_u32 v27, v27, v0, s43
	v_bfe_u32 v0, v31, 16, 1
	v_bfe_u32 v1, v30, 16, 1
	v_lshlrev_b32_e32 v22, 15, v51
	v_mov_b32_e32 v51, v169
	v_add3_u32 v24, v24, v3, s43
	v_add3_u32 v25, v25, v2, s43
	v_bfe_u32 v2, v29, 16, 1
	v_bfe_u32 v3, v28, 16, 1
	v_add3_u32 v30, v30, v1, s43
	v_add3_u32 v31, v31, v0, s43
	v_lshl_add_u64 v[0:1], v[90:91], 0, v[50:51]
	s_mov_b64 s[4:5], 0x2d581800
	s_mov_b32 s2, 0x7060302
	v_add3_u32 v28, v28, v3, s43
	v_add3_u32 v29, v29, v2, s43
	v_lshl_add_u64 v[20:21], v[0:1], 0, s[4:5]
	v_perm_b32 v3, v19, v41, s2
	v_perm_b32 v2, v45, v47, s2
	v_perm_b32 v1, v49, v129, s2
	v_perm_b32 v0, v130, v131, s2
	s_movk_i32 s4, 0xf800
	s_waitcnt lgkmcnt(1)
	v_mfma_f32_16x16x32_bf16 v[8:11], v[4:7], v[0:3], 0
	v_perm_b32 v7, v39, v18, s2
	v_perm_b32 v6, v17, v16, s2
	ds_read_b128 v[16:19], v128 offset:128
	v_perm_b32 v5, v134, v133, s2
	v_perm_b32 v4, v132, v43, s2
	s_waitcnt lgkmcnt(1)
	s_nop 0
	v_mfma_f32_16x16x32_bf16 v[12:15], v[12:15], v[4:7], v[8:11]
	s_nop 2
	v_perm_b32 v11, v27, v26, s2
	v_perm_b32 v10, v25, v24, s2
	ds_read_b128 v[24:27], v128 offset:192
	v_perm_b32 v9, v138, v137, s2
	v_perm_b32 v8, v136, v135, s2
	s_waitcnt lgkmcnt(1)
	s_nop 0
	v_mfma_f32_16x16x32_bf16 v[16:19], v[16:19], v[8:11], v[12:15]
	s_nop 2
	v_perm_b32 v15, v31, v30, s2
	v_perm_b32 v14, v29, v28, s2
	v_perm_b32 v13, v142, v141, s2
	v_perm_b32 v12, v140, v139, s2
	s_waitcnt lgkmcnt(0)
	s_nop 0
	v_mfma_f32_16x16x32_bf16 v[16:19], v[24:27], v[12:15], v[16:19]
	ds_read_b32 v24, v112
	s_waitcnt vmcnt(0) lgkmcnt(0)
	s_nop 5
	v_fma_f32 v16, v23, v24, v16
	v_mul_f32_e32 v24, 0x3d372713, v16
	v_mul_f32_e32 v24, v16, v24
	v_fma_f32 v24, v16, v24, v16
	v_mul_f32_e32 v24, 0x3f4c422a, v24
	v_add_f32_e32 v24, v24, v24
	v_mul_f32_e32 v24, 0x3fb8aa3b, v24
	v_exp_f32_e32 v24, v24
	v_mul_f32_e32 v16, 0.5, v16
	v_add_f32_e32 v24, 1.0, v24
	v_rcp_f32_e32 v24, v24
	s_nop 0
	v_fma_f32 v24, v24, -2.0, 1.0
	v_add_f32_e32 v24, 1.0, v24
	v_mul_f32_e32 v16, v16, v24
	v_bfe_u32 v24, v16, 16, 1
	v_add3_u32 v16, v16, v24, s43
	v_or_b32_e32 v24, v22, v93
	v_lshlrev_b32_e32 v168, 1, v24
	v_lshl_add_u64 v[24:25], v[20:21], 0, v[168:169]
	global_store_short_d16_hi v[24:25], v16, off
	ds_read_b32 v16, v113
	s_waitcnt lgkmcnt(0)
	v_fma_f32 v16, v23, v16, v17
	v_mul_f32_e32 v17, 0x3d372713, v16
	v_mul_f32_e32 v17, v16, v17
	v_fma_f32 v17, v16, v17, v16
	v_mul_f32_e32 v17, 0x3f4c422a, v17
	v_add_f32_e32 v17, v17, v17
	v_mul_f32_e32 v17, 0x3fb8aa3b, v17
	v_exp_f32_e32 v17, v17
	v_mul_f32_e32 v16, 0.5, v16
	v_add_f32_e32 v17, 1.0, v17
	v_rcp_f32_e32 v17, v17
	s_nop 0
	v_fma_f32 v17, v17, -2.0, 1.0
	v_add_f32_e32 v17, 1.0, v17
	v_mul_f32_e32 v16, v16, v17
	v_bfe_u32 v17, v16, 16, 1
	v_add3_u32 v24, v16, v17, s43
	v_or_b32_e32 v16, v22, v94
	v_lshlrev_b32_e32 v168, 1, v16
	v_lshl_add_u64 v[16:17], v[20:21], 0, v[168:169]
	global_store_short_d16_hi v[16:17], v24, off
	ds_read_b32 v16, v114
	ds_read_b128 v[24:27], v128 offset:4416
	s_waitcnt lgkmcnt(1)
	v_fma_f32 v16, v23, v16, v18
	v_mul_f32_e32 v17, 0x3d372713, v16
	v_mul_f32_e32 v17, v16, v17
	v_fma_f32 v17, v16, v17, v16
	v_mul_f32_e32 v17, 0x3f4c422a, v17
	v_add_f32_e32 v17, v17, v17
	v_mul_f32_e32 v17, 0x3fb8aa3b, v17
	v_exp_f32_e32 v17, v17
	v_mul_f32_e32 v16, 0.5, v16
	v_add_f32_e32 v17, 1.0, v17
	v_rcp_f32_e32 v17, v17
	s_nop 0
	v_fma_f32 v17, v17, -2.0, 1.0
	v_add_f32_e32 v17, 1.0, v17
	v_mul_f32_e32 v16, v16, v17
	v_bfe_u32 v17, v16, 16, 1
	v_add3_u32 v18, v16, v17, s43
	v_or_b32_e32 v16, v22, v95
	v_lshlrev_b32_e32 v168, 1, v16
	v_lshl_add_u64 v[16:17], v[20:21], 0, v[168:169]
	global_store_short_d16_hi v[16:17], v18, off
	ds_read_b32 v16, v115
	s_waitcnt lgkmcnt(0)
	v_fmac_f32_e32 v19, v23, v16
	v_mul_f32_e32 v16, 0x3d372713, v19
	v_mul_f32_e32 v16, v19, v16
	v_fma_f32 v16, v19, v16, v19
	v_mul_f32_e32 v16, 0x3f4c422a, v16
	v_add_f32_e32 v16, v16, v16
	v_mul_f32_e32 v16, 0x3fb8aa3b, v16
	v_exp_f32_e32 v16, v16
	v_mul_f32_e32 v17, 0.5, v19
	v_add_f32_e32 v16, 1.0, v16
	v_rcp_f32_e32 v16, v16
	s_nop 0
	v_fma_f32 v16, v16, -2.0, 1.0
	v_add_f32_e32 v16, 1.0, v16
	v_mul_f32_e32 v16, v17, v16
	v_bfe_u32 v17, v16, 16, 1
	v_add3_u32 v18, v16, v17, s43
	v_or_b32_e32 v16, v22, v96
	v_lshlrev_b32_e32 v168, 1, v16
	v_lshl_add_u64 v[16:17], v[20:21], 0, v[168:169]
	global_store_short_d16_hi v[16:17], v18, off
	ds_read_b128 v[16:19], v128 offset:4352
	s_waitcnt lgkmcnt(0)
	v_mfma_f32_16x16x32_bf16 v[16:19], v[16:19], v[0:3], 0
	v_mfma_f32_16x16x32_bf16 v[16:19], v[24:27], v[4:7], v[16:19]
	ds_read_b128 v[24:27], v128 offset:4480
	s_waitcnt lgkmcnt(0)
	v_mfma_f32_16x16x32_bf16 v[16:19], v[24:27], v[8:11], v[16:19]
	ds_read_b128 v[24:27], v128 offset:4544
	s_waitcnt lgkmcnt(0)
	v_mfma_f32_16x16x32_bf16 v[16:19], v[24:27], v[12:15], v[16:19]
	ds_read_b32 v24, v116
	s_waitcnt lgkmcnt(0)
	s_nop 5
	v_fma_f32 v16, v23, v24, v16
	v_mul_f32_e32 v24, 0x3d372713, v16
	v_mul_f32_e32 v24, v16, v24
	v_fma_f32 v24, v16, v24, v16
	v_mul_f32_e32 v24, 0x3f4c422a, v24
	v_add_f32_e32 v24, v24, v24
	v_mul_f32_e32 v24, 0x3fb8aa3b, v24
	v_exp_f32_e32 v24, v24
	v_mul_f32_e32 v16, 0.5, v16
	v_add_f32_e32 v24, 1.0, v24
	v_rcp_f32_e32 v24, v24
	s_nop 0
	v_fma_f32 v24, v24, -2.0, 1.0
	v_add_f32_e32 v24, 1.0, v24
	v_mul_f32_e32 v16, v16, v24
	v_bfe_u32 v24, v16, 16, 1
	v_add3_u32 v16, v16, v24, s43
	v_or_b32_e32 v24, v22, v97
	v_lshlrev_b32_e32 v168, 1, v24
	v_lshl_add_u64 v[24:25], v[20:21], 0, v[168:169]
	global_store_short_d16_hi v[24:25], v16, off
	ds_read_b32 v16, v117
	s_waitcnt lgkmcnt(0)
	v_fma_f32 v16, v23, v16, v17
	v_mul_f32_e32 v17, 0x3d372713, v16
	v_mul_f32_e32 v17, v16, v17
	v_fma_f32 v17, v16, v17, v16
	v_mul_f32_e32 v17, 0x3f4c422a, v17
	v_add_f32_e32 v17, v17, v17
	v_mul_f32_e32 v17, 0x3fb8aa3b, v17
	v_exp_f32_e32 v17, v17
	v_mul_f32_e32 v16, 0.5, v16
	v_add_f32_e32 v17, 1.0, v17
	v_rcp_f32_e32 v17, v17
	s_nop 0
	v_fma_f32 v17, v17, -2.0, 1.0
	v_add_f32_e32 v17, 1.0, v17
	v_mul_f32_e32 v16, v16, v17
	v_bfe_u32 v17, v16, 16, 1
	v_add3_u32 v24, v16, v17, s43
	v_or_b32_e32 v16, v22, v98
	v_lshlrev_b32_e32 v168, 1, v16
	v_lshl_add_u64 v[16:17], v[20:21], 0, v[168:169]
	global_store_short_d16_hi v[16:17], v24, off
	ds_read_b32 v16, v118
	s_waitcnt lgkmcnt(0)
	v_fma_f32 v16, v23, v16, v18
	v_mul_f32_e32 v17, 0x3d372713, v16
	v_mul_f32_e32 v17, v16, v17
	v_fma_f32 v17, v16, v17, v16
	v_mul_f32_e32 v17, 0x3f4c422a, v17
	v_add_f32_e32 v17, v17, v17
	v_mul_f32_e32 v17, 0x3fb8aa3b, v17
	v_exp_f32_e32 v17, v17
	v_mul_f32_e32 v16, 0.5, v16
	v_add_f32_e32 v17, 1.0, v17
	v_rcp_f32_e32 v17, v17
	s_nop 0
	v_fma_f32 v17, v17, -2.0, 1.0
	v_add_f32_e32 v17, 1.0, v17
	v_mul_f32_e32 v16, v16, v17
	v_bfe_u32 v17, v16, 16, 1
	v_add3_u32 v18, v16, v17, s43
	v_or_b32_e32 v16, v22, v99
	v_lshlrev_b32_e32 v168, 1, v16
	v_lshl_add_u64 v[16:17], v[20:21], 0, v[168:169]
	global_store_short_d16_hi v[16:17], v18, off
	ds_read_b32 v16, v119
	s_waitcnt lgkmcnt(0)
	v_fmac_f32_e32 v19, v23, v16
	v_mul_f32_e32 v16, 0x3d372713, v19
	v_mul_f32_e32 v16, v19, v16
	v_fma_f32 v16, v19, v16, v19
	v_mul_f32_e32 v16, 0x3f4c422a, v16
	v_add_f32_e32 v16, v16, v16
	v_mul_f32_e32 v16, 0x3fb8aa3b, v16
	v_exp_f32_e32 v16, v16
	v_mul_f32_e32 v17, 0.5, v19
	v_add_f32_e32 v16, 1.0, v16
	v_rcp_f32_e32 v16, v16
	s_nop 0
	v_fma_f32 v16, v16, -2.0, 1.0
	v_add_f32_e32 v16, 1.0, v16
	v_mul_f32_e32 v16, v17, v16
	v_bfe_u32 v17, v16, 16, 1
	v_add3_u32 v18, v16, v17, s43
	v_or_b32_e32 v16, v22, v100
	v_lshlrev_b32_e32 v168, 1, v16
	v_lshl_add_u64 v[16:17], v[20:21], 0, v[168:169]
	global_store_short_d16_hi v[16:17], v18, off
	s_waitcnt lgkmcnt(0)
	v_mov_b32_e32 v16, v109
.LBB0_882:
	v_add_u32_e32 v248, s4, v110
	v_add_u32_e32 v248, 0x12000, v248
	s_addk_i32 s4, 0x200
	ds_read_b128 v[176:179], v248
	ds_read_b128 v[180:183], v248 offset:16
	ds_read_b128 v[184:187], v248 offset:32
	ds_read_b128 v[188:191], v248 offset:48
	ds_read_b128 v[192:195], v248 offset:64
	ds_read_b128 v[196:199], v248 offset:80
	ds_read_b128 v[200:203], v248 offset:96
	ds_read_b128 v[204:207], v248 offset:112
	ds_read_b128 v[208:211], v248 offset:128
	ds_read_b128 v[212:215], v248 offset:144
	ds_read_b128 v[216:219], v248 offset:160
	ds_read_b128 v[220:223], v248 offset:176
	ds_read_b128 v[156:159], v248 offset:192
	ds_read_b128 v[160:163], v248 offset:208
	ds_read_b128 v[164:167], v248 offset:224
	ds_read_b128 v[232:235], v248 offset:240
	s_waitcnt lgkmcnt(8)
	v_pk_fma_f32 v[240:241], v[176:177], v[54:55], 0 op_sel_hi:[0,1,0]
	v_pk_fma_f32 v[242:243], v[184:185], v[72:73], 0 op_sel_hi:[0,1,0]
	v_pk_fma_f32 v[240:241], v[176:177], v[56:57], v[240:241] op_sel:[1,0,0]
	v_pk_fma_f32 v[242:243], v[184:185], v[74:75], v[242:243] op_sel:[1,0,0]
	v_pk_fma_f32 v[240:241], v[178:179], v[58:59], v[240:241] op_sel_hi:[0,1,1]
	v_pk_fma_f32 v[242:243], v[186:187], v[76:77], v[242:243] op_sel_hi:[0,1,1]
	v_pk_fma_f32 v[240:241], v[178:179], v[60:61], v[240:241] op_sel:[1,0,0]
	v_pk_fma_f32 v[242:243], v[186:187], v[78:79], v[242:243] op_sel:[1,0,0]
	v_pk_fma_f32 v[240:241], v[180:181], v[62:63], v[240:241] op_sel_hi:[0,1,1]
	v_pk_fma_f32 v[242:243], v[188:189], v[80:81], v[242:243] op_sel_hi:[0,1,1]
	v_pk_fma_f32 v[240:241], v[180:181], v[64:65], v[240:241] op_sel:[1,0,0]
	v_pk_fma_f32 v[242:243], v[188:189], v[82:83], v[242:243] op_sel:[1,0,0]
	v_pk_fma_f32 v[240:241], v[182:183], v[68:69], v[240:241] op_sel_hi:[0,1,1]
	v_pk_fma_f32 v[242:243], v[190:191], v[84:85], v[242:243] op_sel_hi:[0,1,1]
	v_pk_fma_f32 v[240:241], v[182:183], v[70:71], v[240:241] op_sel:[1,0,0]
	v_pk_fma_f32 v[242:243], v[190:191], v[86:87], v[242:243] op_sel:[1,0,0]
	v_pk_mul_f32 v[246:247], v[52:53], v[66:67]
	v_pk_add_f32 v[240:241], v[240:241], v[242:243]
	v_pk_fma_f32 v[244:245], v[88:89], v[66:67], v[246:247] op_sel:[0,0,1] op_sel_hi:[1,1,0]
	v_pk_fma_f32 v[66:67], v[88:89], v[66:67], v[246:247] op_sel:[0,0,1] op_sel_hi:[1,1,0] neg_lo:[0,0,1] neg_hi:[0,0,1]
	s_nop 0
	v_mov_b32_e32 v245, v67
	v_pk_add_f32 v[66:67], v[244:245], v[240:241]
	s_nop 0
	v_cvt_pk_bf16_f32 v249, v66, v67
	ds_write_b16_d16_hi v16, v249
	ds_write_b16 v16, v249 offset:128
	v_pk_fma_f32 v[240:241], v[192:193], v[54:55], 0 op_sel_hi:[0,1,0]
	v_pk_fma_f32 v[242:243], v[200:201], v[72:73], 0 op_sel_hi:[0,1,0]
	v_pk_fma_f32 v[240:241], v[192:193], v[56:57], v[240:241] op_sel:[1,0,0]
	v_pk_fma_f32 v[242:243], v[200:201], v[74:75], v[242:243] op_sel:[1,0,0]
	v_pk_fma_f32 v[240:241], v[194:195], v[58:59], v[240:241] op_sel_hi:[0,1,1]
	v_pk_fma_f32 v[242:243], v[202:203], v[76:77], v[242:243] op_sel_hi:[0,1,1]
	v_pk_fma_f32 v[240:241], v[194:195], v[60:61], v[240:241] op_sel:[1,0,0]
	v_pk_fma_f32 v[242:243], v[202:203], v[78:79], v[242:243] op_sel:[1,0,0]
	v_pk_fma_f32 v[240:241], v[196:197], v[62:63], v[240:241] op_sel_hi:[0,1,1]
	v_pk_fma_f32 v[242:243], v[204:205], v[80:81], v[242:243] op_sel_hi:[0,1,1]
	v_pk_fma_f32 v[240:241], v[196:197], v[64:65], v[240:241] op_sel:[1,0,0]
	v_pk_fma_f32 v[242:243], v[204:205], v[82:83], v[242:243] op_sel:[1,0,0]
	v_pk_fma_f32 v[240:241], v[198:199], v[68:69], v[240:241] op_sel_hi:[0,1,1]
	v_pk_fma_f32 v[242:243], v[206:207], v[84:85], v[242:243] op_sel_hi:[0,1,1]
	v_pk_fma_f32 v[240:241], v[198:199], v[70:71], v[240:241] op_sel:[1,0,0]
	v_pk_fma_f32 v[242:243], v[206:207], v[86:87], v[242:243] op_sel:[1,0,0]
	v_pk_mul_f32 v[246:247], v[52:53], v[66:67]
	v_pk_add_f32 v[240:241], v[240:241], v[242:243]
	v_pk_fma_f32 v[244:245], v[88:89], v[66:67], v[246:247] op_sel:[0,0,1] op_sel_hi:[1,1,0]
	v_pk_fma_f32 v[66:67], v[88:89], v[66:67], v[246:247] op_sel:[0,0,1] op_sel_hi:[1,1,0] neg_lo:[0,0,1] neg_hi:[0,0,1]
	s_nop 0
	v_mov_b32_e32 v245, v67
	v_pk_add_f32 v[66:67], v[244:245], v[240:241]
	s_nop 0
	v_cvt_pk_bf16_f32 v249, v66, v67
	ds_write_b16_d16_hi v16, v249 offset:272
	ds_write_b16 v16, v249 offset:400
	ds_read_b128 v[176:179], v248 offset:256
	ds_read_b128 v[180:183], v248 offset:272
	ds_read_b128 v[184:187], v248 offset:288
	ds_read_b128 v[188:191], v248 offset:304
	ds_read_b128 v[192:195], v248 offset:320
	ds_read_b128 v[196:199], v248 offset:336
	ds_read_b128 v[200:203], v248 offset:352
	ds_read_b128 v[204:207], v248 offset:368
	s_waitcnt lgkmcnt(12)
	v_pk_fma_f32 v[240:241], v[208:209], v[54:55], 0 op_sel_hi:[0,1,0]
	v_pk_fma_f32 v[242:243], v[216:217], v[72:73], 0 op_sel_hi:[0,1,0]
	v_pk_fma_f32 v[240:241], v[208:209], v[56:57], v[240:241] op_sel:[1,0,0]
	v_pk_fma_f32 v[242:243], v[216:217], v[74:75], v[242:243] op_sel:[1,0,0]
	v_pk_fma_f32 v[240:241], v[210:211], v[58:59], v[240:241] op_sel_hi:[0,1,1]
	v_pk_fma_f32 v[242:243], v[218:219], v[76:77], v[242:243] op_sel_hi:[0,1,1]
	v_pk_fma_f32 v[240:241], v[210:211], v[60:61], v[240:241] op_sel:[1,0,0]
	v_pk_fma_f32 v[242:243], v[218:219], v[78:79], v[242:243] op_sel:[1,0,0]
	v_pk_fma_f32 v[240:241], v[212:213], v[62:63], v[240:241] op_sel_hi:[0,1,1]
	v_pk_fma_f32 v[242:243], v[220:221], v[80:81], v[242:243] op_sel_hi:[0,1,1]
	v_pk_fma_f32 v[240:241], v[212:213], v[64:65], v[240:241] op_sel:[1,0,0]
	v_pk_fma_f32 v[242:243], v[220:221], v[82:83], v[242:243] op_sel:[1,0,0]
	v_pk_fma_f32 v[240:241], v[214:215], v[68:69], v[240:241] op_sel_hi:[0,1,1]
	v_pk_fma_f32 v[242:243], v[222:223], v[84:85], v[242:243] op_sel_hi:[0,1,1]
	v_pk_fma_f32 v[240:241], v[214:215], v[70:71], v[240:241] op_sel:[1,0,0]
	v_pk_fma_f32 v[242:243], v[222:223], v[86:87], v[242:243] op_sel:[1,0,0]
	v_pk_mul_f32 v[246:247], v[52:53], v[66:67]
	v_pk_add_f32 v[240:241], v[240:241], v[242:243]
	v_pk_fma_f32 v[244:245], v[88:89], v[66:67], v[246:247] op_sel:[0,0,1] op_sel_hi:[1,1,0]
	v_pk_fma_f32 v[66:67], v[88:89], v[66:67], v[246:247] op_sel:[0,0,1] op_sel_hi:[1,1,0] neg_lo:[0,0,1] neg_hi:[0,0,1]
	s_nop 0
	v_mov_b32_e32 v245, v67
	v_pk_add_f32 v[66:67], v[244:245], v[240:241]
	s_nop 0
	v_cvt_pk_bf16_f32 v249, v66, v67
	ds_write_b16_d16_hi v16, v249 offset:544
	ds_write_b16 v16, v249 offset:672
	v_pk_fma_f32 v[240:241], v[156:157], v[54:55], 0 op_sel_hi:[0,1,0]
	v_pk_fma_f32 v[242:243], v[164:165], v[72:73], 0 op_sel_hi:[0,1,0]
	v_pk_fma_f32 v[240:241], v[156:157], v[56:57], v[240:241] op_sel:[1,0,0]
	v_pk_fma_f32 v[242:243], v[164:165], v[74:75], v[242:243] op_sel:[1,0,0]
	v_pk_fma_f32 v[240:241], v[158:159], v[58:59], v[240:241] op_sel_hi:[0,1,1]
	v_pk_fma_f32 v[242:243], v[166:167], v[76:77], v[242:243] op_sel_hi:[0,1,1]
	v_pk_fma_f32 v[240:241], v[158:159], v[60:61], v[240:241] op_sel:[1,0,0]
	v_pk_fma_f32 v[242:243], v[166:167], v[78:79], v[242:243] op_sel:[1,0,0]
	v_pk_fma_f32 v[240:241], v[160:161], v[62:63], v[240:241] op_sel_hi:[0,1,1]
	v_pk_fma_f32 v[242:243], v[232:233], v[80:81], v[242:243] op_sel_hi:[0,1,1]
	v_pk_fma_f32 v[240:241], v[160:161], v[64:65], v[240:241] op_sel:[1,0,0]
	v_pk_fma_f32 v[242:243], v[232:233], v[82:83], v[242:243] op_sel:[1,0,0]
	v_pk_fma_f32 v[240:241], v[162:163], v[68:69], v[240:241] op_sel_hi:[0,1,1]
	v_pk_fma_f32 v[242:243], v[234:235], v[84:85], v[242:243] op_sel_hi:[0,1,1]
	v_pk_fma_f32 v[240:241], v[162:163], v[70:71], v[240:241] op_sel:[1,0,0]
	v_pk_fma_f32 v[242:243], v[234:235], v[86:87], v[242:243] op_sel:[1,0,0]
	v_pk_mul_f32 v[246:247], v[52:53], v[66:67]
	v_pk_add_f32 v[240:241], v[240:241], v[242:243]
	v_pk_fma_f32 v[244:245], v[88:89], v[66:67], v[246:247] op_sel:[0,0,1] op_sel_hi:[1,1,0]
	v_pk_fma_f32 v[66:67], v[88:89], v[66:67], v[246:247] op_sel:[0,0,1] op_sel_hi:[1,1,0] neg_lo:[0,0,1] neg_hi:[0,0,1]
	s_nop 0
	v_mov_b32_e32 v245, v67
	v_pk_add_f32 v[66:67], v[244:245], v[240:241]
	s_nop 0
	v_cvt_pk_bf16_f32 v249, v66, v67
	ds_write_b16_d16_hi v16, v249 offset:816
	ds_write_b16 v16, v249 offset:944
	ds_read_b128 v[208:211], v248 offset:384
	ds_read_b128 v[212:215], v248 offset:400
	ds_read_b128 v[216:219], v248 offset:416
	ds_read_b128 v[220:223], v248 offset:432
	ds_read_b128 v[156:159], v248 offset:448
	ds_read_b128 v[160:163], v248 offset:464
	ds_read_b128 v[164:167], v248 offset:480
	ds_read_b128 v[232:235], v248 offset:496
	s_waitcnt lgkmcnt(12)
	v_pk_fma_f32 v[240:241], v[176:177], v[54:55], 0 op_sel_hi:[0,1,0]
	v_pk_fma_f32 v[242:243], v[184:185], v[72:73], 0 op_sel_hi:[0,1,0]
	v_pk_fma_f32 v[240:241], v[176:177], v[56:57], v[240:241] op_sel:[1,0,0]
	v_pk_fma_f32 v[242:243], v[184:185], v[74:75], v[242:243] op_sel:[1,0,0]
	v_pk_fma_f32 v[240:241], v[178:179], v[58:59], v[240:241] op_sel_hi:[0,1,1]
	v_pk_fma_f32 v[242:243], v[186:187], v[76:77], v[242:243] op_sel_hi:[0,1,1]
	v_pk_fma_f32 v[240:241], v[178:179], v[60:61], v[240:241] op_sel:[1,0,0]
	v_pk_fma_f32 v[242:243], v[186:187], v[78:79], v[242:243] op_sel:[1,0,0]
	v_pk_fma_f32 v[240:241], v[180:181], v[62:63], v[240:241] op_sel_hi:[0,1,1]
	v_pk_fma_f32 v[242:243], v[188:189], v[80:81], v[242:243] op_sel_hi:[0,1,1]
	v_pk_fma_f32 v[240:241], v[180:181], v[64:65], v[240:241] op_sel:[1,0,0]
	v_pk_fma_f32 v[242:243], v[188:189], v[82:83], v[242:243] op_sel:[1,0,0]
	v_pk_fma_f32 v[240:241], v[182:183], v[68:69], v[240:241] op_sel_hi:[0,1,1]
	v_pk_fma_f32 v[242:243], v[190:191], v[84:85], v[242:243] op_sel_hi:[0,1,1]
	v_pk_fma_f32 v[240:241], v[182:183], v[70:71], v[240:241] op_sel:[1,0,0]
	v_pk_fma_f32 v[242:243], v[190:191], v[86:87], v[242:243] op_sel:[1,0,0]
	v_pk_mul_f32 v[246:247], v[52:53], v[66:67]
	v_pk_add_f32 v[240:241], v[240:241], v[242:243]
	v_pk_fma_f32 v[244:245], v[88:89], v[66:67], v[246:247] op_sel:[0,0,1] op_sel_hi:[1,1,0]
	v_pk_fma_f32 v[66:67], v[88:89], v[66:67], v[246:247] op_sel:[0,0,1] op_sel_hi:[1,1,0] neg_lo:[0,0,1] neg_hi:[0,0,1]
	s_nop 0
	v_mov_b32_e32 v245, v67
	v_pk_add_f32 v[66:67], v[244:245], v[240:241]
	s_nop 0
	v_cvt_pk_bf16_f32 v249, v66, v67
	ds_write_b16_d16_hi v16, v249 offset:1088
	ds_write_b16 v16, v249 offset:1216
	v_pk_fma_f32 v[240:241], v[192:193], v[54:55], 0 op_sel_hi:[0,1,0]
	v_pk_fma_f32 v[242:243], v[200:201], v[72:73], 0 op_sel_hi:[0,1,0]
	v_pk_fma_f32 v[240:241], v[192:193], v[56:57], v[240:241] op_sel:[1,0,0]
	v_pk_fma_f32 v[242:243], v[200:201], v[74:75], v[242:243] op_sel:[1,0,0]
	v_pk_fma_f32 v[240:241], v[194:195], v[58:59], v[240:241] op_sel_hi:[0,1,1]
	v_pk_fma_f32 v[242:243], v[202:203], v[76:77], v[242:243] op_sel_hi:[0,1,1]
	v_pk_fma_f32 v[240:241], v[194:195], v[60:61], v[240:241] op_sel:[1,0,0]
	v_pk_fma_f32 v[242:243], v[202:203], v[78:79], v[242:243] op_sel:[1,0,0]
	v_pk_fma_f32 v[240:241], v[196:197], v[62:63], v[240:241] op_sel_hi:[0,1,1]
	v_pk_fma_f32 v[242:243], v[204:205], v[80:81], v[242:243] op_sel_hi:[0,1,1]
	v_pk_fma_f32 v[240:241], v[196:197], v[64:65], v[240:241] op_sel:[1,0,0]
	v_pk_fma_f32 v[242:243], v[204:205], v[82:83], v[242:243] op_sel:[1,0,0]
	v_pk_fma_f32 v[240:241], v[198:199], v[68:69], v[240:241] op_sel_hi:[0,1,1]
	v_pk_fma_f32 v[242:243], v[206:207], v[84:85], v[242:243] op_sel_hi:[0,1,1]
	v_pk_fma_f32 v[240:241], v[198:199], v[70:71], v[240:241] op_sel:[1,0,0]
	v_pk_fma_f32 v[242:243], v[206:207], v[86:87], v[242:243] op_sel:[1,0,0]
	v_pk_mul_f32 v[246:247], v[52:53], v[66:67]
	v_pk_add_f32 v[240:241], v[240:241], v[242:243]
	v_pk_fma_f32 v[244:245], v[88:89], v[66:67], v[246:247] op_sel:[0,0,1] op_sel_hi:[1,1,0]
	v_pk_fma_f32 v[66:67], v[88:89], v[66:67], v[246:247] op_sel:[0,0,1] op_sel_hi:[1,1,0] neg_lo:[0,0,1] neg_hi:[0,0,1]
	s_nop 0
	v_mov_b32_e32 v245, v67
	v_pk_add_f32 v[66:67], v[244:245], v[240:241]
	s_nop 0
	v_cvt_pk_bf16_f32 v249, v66, v67
	ds_write_b16_d16_hi v16, v249 offset:1360
	ds_write_b16 v16, v249 offset:1488
	s_waitcnt lgkmcnt(4)
	v_pk_fma_f32 v[240:241], v[208:209], v[54:55], 0 op_sel_hi:[0,1,0]
	v_pk_fma_f32 v[242:243], v[216:217], v[72:73], 0 op_sel_hi:[0,1,0]
	v_pk_fma_f32 v[240:241], v[208:209], v[56:57], v[240:241] op_sel:[1,0,0]
	v_pk_fma_f32 v[242:243], v[216:217], v[74:75], v[242:243] op_sel:[1,0,0]
	v_pk_fma_f32 v[240:241], v[210:211], v[58:59], v[240:241] op_sel_hi:[0,1,1]
	v_pk_fma_f32 v[242:243], v[218:219], v[76:77], v[242:243] op_sel_hi:[0,1,1]
	v_pk_fma_f32 v[240:241], v[210:211], v[60:61], v[240:241] op_sel:[1,0,0]
	v_pk_fma_f32 v[242:243], v[218:219], v[78:79], v[242:243] op_sel:[1,0,0]
	v_pk_fma_f32 v[240:241], v[212:213], v[62:63], v[240:241] op_sel_hi:[0,1,1]
	v_pk_fma_f32 v[242:243], v[220:221], v[80:81], v[242:243] op_sel_hi:[0,1,1]
	v_pk_fma_f32 v[240:241], v[212:213], v[64:65], v[240:241] op_sel:[1,0,0]
	v_pk_fma_f32 v[242:243], v[220:221], v[82:83], v[242:243] op_sel:[1,0,0]
	v_pk_fma_f32 v[240:241], v[214:215], v[68:69], v[240:241] op_sel_hi:[0,1,1]
	v_pk_fma_f32 v[242:243], v[222:223], v[84:85], v[242:243] op_sel_hi:[0,1,1]
	v_pk_fma_f32 v[240:241], v[214:215], v[70:71], v[240:241] op_sel:[1,0,0]
	v_pk_fma_f32 v[242:243], v[222:223], v[86:87], v[242:243] op_sel:[1,0,0]
	v_pk_mul_f32 v[246:247], v[52:53], v[66:67]
	v_pk_add_f32 v[240:241], v[240:241], v[242:243]
	v_pk_fma_f32 v[244:245], v[88:89], v[66:67], v[246:247] op_sel:[0,0,1] op_sel_hi:[1,1,0]
	v_pk_fma_f32 v[66:67], v[88:89], v[66:67], v[246:247] op_sel:[0,0,1] op_sel_hi:[1,1,0] neg_lo:[0,0,1] neg_hi:[0,0,1]
	s_nop 0
	v_mov_b32_e32 v245, v67
	v_pk_add_f32 v[66:67], v[244:245], v[240:241]
	s_nop 0
	v_cvt_pk_bf16_f32 v249, v66, v67
	ds_write_b16_d16_hi v16, v249 offset:1632
	ds_write_b16 v16, v249 offset:1760
	v_pk_fma_f32 v[240:241], v[156:157], v[54:55], 0 op_sel_hi:[0,1,0]
	v_pk_fma_f32 v[242:243], v[164:165], v[72:73], 0 op_sel_hi:[0,1,0]
	v_pk_fma_f32 v[240:241], v[156:157], v[56:57], v[240:241] op_sel:[1,0,0]
	v_pk_fma_f32 v[242:243], v[164:165], v[74:75], v[242:243] op_sel:[1,0,0]
	v_pk_fma_f32 v[240:241], v[158:159], v[58:59], v[240:241] op_sel_hi:[0,1,1]
	v_pk_fma_f32 v[242:243], v[166:167], v[76:77], v[242:243] op_sel_hi:[0,1,1]
	v_pk_fma_f32 v[240:241], v[158:159], v[60:61], v[240:241] op_sel:[1,0,0]
	v_pk_fma_f32 v[242:243], v[166:167], v[78:79], v[242:243] op_sel:[1,0,0]
	v_pk_fma_f32 v[240:241], v[160:161], v[62:63], v[240:241] op_sel_hi:[0,1,1]
	v_pk_fma_f32 v[242:243], v[232:233], v[80:81], v[242:243] op_sel_hi:[0,1,1]
	v_pk_fma_f32 v[240:241], v[160:161], v[64:65], v[240:241] op_sel:[1,0,0]
	v_pk_fma_f32 v[242:243], v[232:233], v[82:83], v[242:243] op_sel:[1,0,0]
	v_pk_fma_f32 v[240:241], v[162:163], v[68:69], v[240:241] op_sel_hi:[0,1,1]
	v_pk_fma_f32 v[242:243], v[234:235], v[84:85], v[242:243] op_sel_hi:[0,1,1]
	v_pk_fma_f32 v[240:241], v[162:163], v[70:71], v[240:241] op_sel:[1,0,0]
	v_pk_fma_f32 v[242:243], v[234:235], v[86:87], v[242:243] op_sel:[1,0,0]
	v_pk_mul_f32 v[246:247], v[52:53], v[66:67]
	v_pk_add_f32 v[240:241], v[240:241], v[242:243]
	v_pk_fma_f32 v[244:245], v[88:89], v[66:67], v[246:247] op_sel:[0,0,1] op_sel_hi:[1,1,0]
	v_pk_fma_f32 v[66:67], v[88:89], v[66:67], v[246:247] op_sel:[0,0,1] op_sel_hi:[1,1,0] neg_lo:[0,0,1] neg_hi:[0,0,1]
	s_nop 0
	v_mov_b32_e32 v245, v67
	v_pk_add_f32 v[66:67], v[244:245], v[240:241]
	s_nop 0
	v_cvt_pk_bf16_f32 v249, v66, v67
	ds_write_b16_d16_hi v16, v249 offset:1904
	ds_write_b16 v16, v249 offset:2032
	v_add_u32_e32 v16, 0x880, v16
	s_cmp_lg_u32 s4, 0
	s_cbranch_scc1 .LBB0_882
	s_waitcnt lgkmcnt(0)
	ds_read_b128 v[16:19], v128
	ds_read_b128 v[24:27], v128 offset:64
	v_add_u32_e32 v33, s19, v33
	s_movk_i32 s2, 0xfff
	v_cmp_lt_i32_e32 vcc, s2, v33
	s_or_b64 s[22:23], vcc, s[22:23]
	s_waitcnt lgkmcnt(1)
	v_mfma_f32_16x16x32_bf16 v[16:19], v[16:19], v[0:3], 0
	s_waitcnt lgkmcnt(0)
	v_mfma_f32_16x16x32_bf16 v[16:19], v[24:27], v[4:7], v[16:19]
	ds_read_b128 v[24:27], v128 offset:128
	s_waitcnt lgkmcnt(0)
	v_mfma_f32_16x16x32_bf16 v[16:19], v[24:27], v[8:11], v[16:19]
	ds_read_b128 v[24:27], v128 offset:192
	s_waitcnt lgkmcnt(0)
	v_mfma_f32_16x16x32_bf16 v[16:19], v[24:27], v[12:15], v[16:19]
	ds_read_b32 v24, v120
	s_waitcnt lgkmcnt(0)
	s_nop 5
	v_fma_f32 v16, v23, v24, v16
	v_mul_f32_e32 v24, 0x3d372713, v16
	v_mul_f32_e32 v24, v16, v24
	v_fma_f32 v24, v16, v24, v16
	v_mul_f32_e32 v24, 0x3f4c422a, v24
	v_add_f32_e32 v24, v24, v24
	v_mul_f32_e32 v24, 0x3fb8aa3b, v24
	v_exp_f32_e32 v24, v24
	v_mul_f32_e32 v16, 0.5, v16
	v_add_f32_e32 v24, 1.0, v24
	v_rcp_f32_e32 v24, v24
	s_nop 0
	v_fma_f32 v24, v24, -2.0, 1.0
	v_add_f32_e32 v24, 1.0, v24
	v_mul_f32_e32 v16, v16, v24
	v_bfe_u32 v24, v16, 16, 1
	v_add3_u32 v16, v16, v24, s43
	v_or_b32_e32 v24, v22, v101
	v_lshlrev_b32_e32 v168, 1, v24
	v_lshl_add_u64 v[24:25], v[20:21], 0, v[168:169]
	global_store_short_d16_hi v[24:25], v16, off
	ds_read_b32 v16, v121
	s_waitcnt lgkmcnt(0)
	v_fma_f32 v16, v23, v16, v17
	v_mul_f32_e32 v17, 0x3d372713, v16
	v_mul_f32_e32 v17, v16, v17
	v_fma_f32 v17, v16, v17, v16
	v_mul_f32_e32 v17, 0x3f4c422a, v17
	v_add_f32_e32 v17, v17, v17
	v_mul_f32_e32 v17, 0x3fb8aa3b, v17
	v_exp_f32_e32 v17, v17
	v_mul_f32_e32 v16, 0.5, v16
	v_add_f32_e32 v17, 1.0, v17
	v_rcp_f32_e32 v17, v17
	s_nop 0
	v_fma_f32 v17, v17, -2.0, 1.0
	v_add_f32_e32 v17, 1.0, v17
	v_mul_f32_e32 v16, v16, v17
	v_bfe_u32 v17, v16, 16, 1
	v_add3_u32 v24, v16, v17, s43
	v_or_b32_e32 v16, v22, v102
	v_lshlrev_b32_e32 v168, 1, v16
	v_lshl_add_u64 v[16:17], v[20:21], 0, v[168:169]
	global_store_short_d16_hi v[16:17], v24, off
	ds_read_b32 v16, v122
	s_waitcnt lgkmcnt(0)
	v_fma_f32 v16, v23, v16, v18
	v_mul_f32_e32 v17, 0x3d372713, v16
	v_mul_f32_e32 v17, v16, v17
	v_fma_f32 v17, v16, v17, v16
	v_mul_f32_e32 v17, 0x3f4c422a, v17
	v_add_f32_e32 v17, v17, v17
	v_mul_f32_e32 v17, 0x3fb8aa3b, v17
	v_exp_f32_e32 v17, v17
	v_mul_f32_e32 v16, 0.5, v16
	v_add_f32_e32 v17, 1.0, v17
	v_rcp_f32_e32 v17, v17
	s_nop 0
	v_fma_f32 v17, v17, -2.0, 1.0
	v_add_f32_e32 v17, 1.0, v17
	v_mul_f32_e32 v16, v16, v17
	v_bfe_u32 v17, v16, 16, 1
	v_add3_u32 v18, v16, v17, s43
	v_or_b32_e32 v16, v22, v103
	v_lshlrev_b32_e32 v168, 1, v16
	v_lshl_add_u64 v[16:17], v[20:21], 0, v[168:169]
	global_store_short_d16_hi v[16:17], v18, off
	ds_read_b32 v16, v123
	s_waitcnt lgkmcnt(0)
	v_fmac_f32_e32 v19, v23, v16
	v_mul_f32_e32 v16, 0x3d372713, v19
	v_mul_f32_e32 v16, v19, v16
	v_fma_f32 v16, v19, v16, v19
	v_mul_f32_e32 v16, 0x3f4c422a, v16
	v_add_f32_e32 v16, v16, v16
	v_mul_f32_e32 v16, 0x3fb8aa3b, v16
	v_exp_f32_e32 v16, v16
	v_mul_f32_e32 v17, 0.5, v19
	v_add_f32_e32 v16, 1.0, v16
	v_rcp_f32_e32 v16, v16
	s_nop 0
	v_fma_f32 v16, v16, -2.0, 1.0
	v_add_f32_e32 v16, 1.0, v16
	v_mul_f32_e32 v16, v17, v16
	v_bfe_u32 v17, v16, 16, 1
	v_add3_u32 v18, v16, v17, s43
	v_or_b32_e32 v16, v22, v104
	v_lshlrev_b32_e32 v168, 1, v16
	v_lshl_add_u64 v[16:17], v[20:21], 0, v[168:169]
	global_store_short_d16_hi v[16:17], v18, off
	ds_read_b128 v[16:19], v128 offset:4352
	s_waitcnt lgkmcnt(0)
	v_mfma_f32_16x16x32_bf16 v[0:3], v[16:19], v[0:3], 0
	ds_read_b128 v[16:19], v128 offset:4416
	s_waitcnt lgkmcnt(0)
	v_mfma_f32_16x16x32_bf16 v[0:3], v[16:19], v[4:7], v[0:3]
	ds_read_b128 v[4:7], v128 offset:4480
	s_waitcnt lgkmcnt(0)
	v_mfma_f32_16x16x32_bf16 v[0:3], v[4:7], v[8:11], v[0:3]
	ds_read_b128 v[4:7], v128 offset:4544
	s_waitcnt lgkmcnt(0)
	v_mfma_f32_16x16x32_bf16 v[0:3], v[4:7], v[12:15], v[0:3]
	ds_read_b32 v4, v124
	s_waitcnt lgkmcnt(0)
	s_nop 5
	v_fma_f32 v0, v23, v4, v0
	v_mul_f32_e32 v4, 0x3d372713, v0
	v_mul_f32_e32 v4, v0, v4
	v_fma_f32 v4, v0, v4, v0
	v_mul_f32_e32 v4, 0x3f4c422a, v4
	v_add_f32_e32 v4, v4, v4
	v_mul_f32_e32 v4, 0x3fb8aa3b, v4
	v_exp_f32_e32 v4, v4
	v_mul_f32_e32 v0, 0.5, v0
	v_add_f32_e32 v4, 1.0, v4
	v_rcp_f32_e32 v4, v4
	s_nop 0
	v_fma_f32 v4, v4, -2.0, 1.0
	v_add_f32_e32 v4, 1.0, v4
	v_mul_f32_e32 v0, v0, v4
	v_bfe_u32 v4, v0, 16, 1
	v_add3_u32 v0, v0, v4, s43
	v_or_b32_e32 v4, v22, v105
	v_lshlrev_b32_e32 v168, 1, v4
	v_lshl_add_u64 v[4:5], v[20:21], 0, v[168:169]
	global_store_short_d16_hi v[4:5], v0, off
	ds_read_b32 v0, v125
	s_waitcnt lgkmcnt(0)
	v_fma_f32 v0, v23, v0, v1
	v_mul_f32_e32 v1, 0x3d372713, v0
	v_mul_f32_e32 v1, v0, v1
	v_fma_f32 v1, v0, v1, v0
	v_mul_f32_e32 v1, 0x3f4c422a, v1
	v_add_f32_e32 v1, v1, v1
	v_mul_f32_e32 v1, 0x3fb8aa3b, v1
	v_exp_f32_e32 v1, v1
	v_mul_f32_e32 v0, 0.5, v0
	v_add_f32_e32 v1, 1.0, v1
	v_rcp_f32_e32 v1, v1
	s_nop 0
	v_fma_f32 v1, v1, -2.0, 1.0
	v_add_f32_e32 v1, 1.0, v1
	v_mul_f32_e32 v0, v0, v1
	v_bfe_u32 v1, v0, 16, 1
	v_add3_u32 v4, v0, v1, s43
	v_or_b32_e32 v0, v22, v106
	v_lshlrev_b32_e32 v168, 1, v0
	v_lshl_add_u64 v[0:1], v[20:21], 0, v[168:169]
	global_store_short_d16_hi v[0:1], v4, off
	ds_read_b32 v0, v126
	s_waitcnt lgkmcnt(0)
	v_fma_f32 v0, v23, v0, v2
	v_mul_f32_e32 v1, 0x3d372713, v0
	v_mul_f32_e32 v1, v0, v1
	v_fma_f32 v1, v0, v1, v0
	v_mul_f32_e32 v1, 0x3f4c422a, v1
	v_add_f32_e32 v1, v1, v1
	v_mul_f32_e32 v1, 0x3fb8aa3b, v1
	v_exp_f32_e32 v1, v1
	v_mul_f32_e32 v0, 0.5, v0
	v_add_f32_e32 v1, 1.0, v1
	v_rcp_f32_e32 v1, v1
	s_nop 0
	v_fma_f32 v1, v1, -2.0, 1.0
	v_add_f32_e32 v1, 1.0, v1
	v_mul_f32_e32 v0, v0, v1
	v_bfe_u32 v1, v0, 16, 1
	v_add3_u32 v2, v0, v1, s43
	v_or_b32_e32 v0, v22, v107
	v_lshlrev_b32_e32 v168, 1, v0
	v_lshl_add_u64 v[0:1], v[20:21], 0, v[168:169]
	global_store_short_d16_hi v[0:1], v2, off
	ds_read_b32 v0, v127
	s_waitcnt lgkmcnt(0)
	v_fmac_f32_e32 v3, v23, v0
	v_mul_f32_e32 v0, 0x3d372713, v3
	v_mul_f32_e32 v0, v3, v0
	v_fma_f32 v0, v3, v0, v3
	v_mul_f32_e32 v0, 0x3f4c422a, v0
	v_add_f32_e32 v0, v0, v0
	v_mul_f32_e32 v0, 0x3fb8aa3b, v0
	v_exp_f32_e32 v0, v0
	v_mul_f32_e32 v1, 0.5, v3
	v_add_f32_e32 v0, 1.0, v0
	v_rcp_f32_e32 v0, v0
	s_nop 0
	v_fma_f32 v0, v0, -2.0, 1.0
	v_add_f32_e32 v0, 1.0, v0
	v_mul_f32_e32 v0, v1, v0
	v_bfe_u32 v1, v0, 16, 1
	v_add3_u32 v2, v0, v1, s43
	v_or_b32_e32 v0, v22, v108
	v_lshlrev_b32_e32 v168, 1, v0
	v_lshl_add_u64 v[0:1], v[20:21], 0, v[168:169]
	global_store_short_d16_hi v[0:1], v2, off
	s_waitcnt lgkmcnt(0)
	s_andn2_b64 exec, exec, s[22:23]
	s_cbranch_execnz .LBB0_859
